# GEMM: one static s_setprio 1 for the trailing wave half (wr==1) at each GEMM prologue, reset to 0 at attention unit start; no per-segment toggles
# baseline (speedup 1.0000x reference)
;     __host__ __device__ bool next(int i, Unit& u) const { const int nr = nwg / G; if (i >= nr) return false; return StaticOrder::next(nr - 1 - i, u); }
; #define PG8_STAGE(bufoff, gbase, voff) do { _Pragma("unroll") for (int _i = 0; _i < 2; ++_i) \
;         __builtin_amdgcn_global_load_lds((const unsigned*)((const char*)(gbase) + (voff)[_i]), (PG8_LAS unsigned*)(lds + (bufoff) + ldsw + _i * 8192), 16, 0, 0); } while (0)
; template <class Epi, class Sched, bool ALIGN_EPI = false, bool SP2 = false>
; __device__ __forceinline__ void gemm_phase(PG8_LAS unsigned char* lds, const Gemm g, const Sched& S, const Epi& E) {
;     ...
;     const int tid = tid_o, wid = __builtin_amdgcn_readfirstlane(tid >> 6), lane = tid & 63, wr = wid >> 2, wc = wid & 3, fr = lane & 15, fq = lane >> 4;
;     const int K = g.K, nt = K / BK;
;     unsigned voffA[2], voffB[2];
; #pragma unroll
;     for (int i = 0; i < 2; ++i) { int R, C; stage_rc(tid * 16 + i * 8192, R, C); const int Rb = Epi::PERM ? ((R & ~31) + perm32(R & 31)) : R;
;         voffA[i] = (unsigned)(R * K + C) * 2u; voffB[i] = (unsigned)(Rb * K + C) * 2u; }
;     const size_t kstep = (size_t)(BK * 2);
;     const size_t hstep = (size_t)HALF * K * 2;
;     const size_t tstep = 2 * hstep;
;     const unsigned ldsw = (unsigned)wid * 1024u;
;     const int aoff = lds_byte(wr * 64 + fr, fq * 8), boff = lds_byte(wc * 32 + fr, fq * 8);
;     ...
;     Unit cur, nxt; int ui = 0;
;     if (!S.next(0, cur)) return;
;     f32x4 acc[2][2][4][2];
; #pragma unroll
;     for (int a = 0; a < 2; ++a)
; #pragma unroll
;         for (int b = 0; b < 2; ++b)
; #pragma unroll
;             for (int m = 0; m < 4; ++m)
; #pragma unroll
;                 for (int n = 0; n < 2; ++n) acc[a][b][m][n] = (f32x4){0.f, 0.f, 0.f, 0.f};
;     bf16x8 At[4][2], B0[2][2], B1[2][2];
;     const char* cA = (const char*)g.A + (size_t)cur.pm * tstep; const char* cB = (const char*)g.Bt + (size_t)cur.pn * tstep;
;     S.a_ready(cur);
;     if constexpr (SP2) {
;         PG8_STAGE(PG8_SB(0, 0), cB, voffB); PG8_STAGE(PG8_SB(0, 1), cB + hstep, voffB); PG8_STAGE(PG8_SA(0, 0), cA, voffA); PG8_STAGE(PG8_SA(0, 1), cA + hstep, voffA);
;         if (wr == 1) PG8_BAR;
;         PG8_WAIT_V(2); PG8_BAR;
;         PG8_STAGE(PG8_SB(1, 0), cB + kstep, voffB); PG8_STAGE(PG8_SA(1, 0), cA + kstep, voffA); PG8_STAGE(PG8_SB(1, 1), cB + hstep + kstep, voffB);
.LBB0_170:
	v_readlane_b32 s6, v253, 56
	v_readlane_b32 s7, v253, 57
	s_add_u32 s0, s6, s0
	s_addc_u32 s1, s7, s1
	s_add_u32 s4, s0, s4
	v_writelane_b32 v254, s5, 53
	s_addc_u32 s5, s1, 0
	v_writelane_b32 v254, s4, 54
	s_andn2_b64 vcc, exec, s[52:53]
	s_nop 0
	v_writelane_b32 v254, s5, 55
	s_cbranch_vccnz .LBB0_410
	v_readlane_b32 s0, v252, 42
	v_writelane_b32 v254, s63, 62
	v_mov_b32_e32 v6, v202
	v_readlane_b32 s1, v252, 43
	v_readlane_b32 s62, v252, 34
	s_andn2_b64 vcc, exec, s[0:1]
	v_readfirstlane_b32 s4, v6
	v_readlane_b32 s63, v252, 35
	s_cbranch_vccnz .LBB0_412
	v_lshlrev_b32_e32 v0, 4, v6
	s_waitcnt lgkmcnt(0)
	v_add_u32_e32 v1, 0x2000, v0
	v_ashrrev_i32_e32 v2, 31, v1
	v_lshrrev_b32_e32 v2, 22, v2
	v_add_u32_e32 v2, v1, v2
	v_ashrrev_i32_e32 v4, 10, v2
	v_mul_i32_i24_e32 v2, 0x400, v4
	v_sub_u32_e32 v1, v1, v2
	v_lshrrev_b32_e32 v2, 4, v1
	v_bitop3_b32 v1, v2, v1, 32 bitop3:0x6c
	v_ashrrev_i32_e32 v2, 31, v1
	v_lshrrev_b32_e32 v2, 26, v2
	v_add_u32_e32 v2, v1, v2
	v_lshlrev_b32_e32 v3, 3, v4
	v_ashrrev_i32_e32 v5, 6, v2
	v_and_b32_e32 v3, -16, v3
	v_add_u32_e32 v3, v5, v3
	v_and_b32_e32 v7, 3, v5
	s_mov_b32 s0, 0x1fffe0
	v_lshrrev_b32_e32 v8, 2, v3
	v_lshlrev_b32_e32 v9, 1, v3
	v_and_b32_e32 v2, 0xc0, v2
	v_and_or_b32 v7, v3, s0, v7
	v_and_b32_e32 v8, 4, v8
	v_and_b32_e32 v9, 24, v9
	v_sub_u32_e32 v1, v1, v2
	v_mov_b32_e32 v12, 1
	v_or3_b32 v8, v7, v8, v9
	v_lshlrev_b32_e32 v7, 5, v4
	v_ashrrev_i16_sdwa v1, v12, sext(v1) dst_sel:DWORD dst_unused:UNUSED_PAD src0_sel:DWORD src1_sel:BYTE_0
	v_and_b32_e32 v9, 32, v7
	v_bfe_i32 v7, v1, 0, 16
	v_add_lshl_u32 v1, v9, v7, 1
	v_lshl_add_u32 v128, v8, 11, v1
	v_lshl_add_u32 v130, v3, 11, v1
	v_bfe_i32 v1, v6, 27, 1
	v_lshrrev_b32_e32 v1, 22, v1
	v_add_u32_e32 v1, v0, v1
	v_and_b32_e32 v1, 0xfffffc00, v1
	v_sub_u32_e32 v0, v0, v1
	v_lshrrev_b32_e32 v1, 4, v0
	v_ashrrev_i32_e32 v2, 31, v6
	v_bitop3_b32 v0, v1, v0, 32 bitop3:0x6c
	v_lshrrev_b32_e32 v2, 26, v2
	v_ashrrev_i32_e32 v1, 31, v0
	v_add_u32_e32 v2, v6, v2
	v_lshrrev_b32_e32 v1, 26, v1
	v_ashrrev_i32_e32 v9, 6, v2
	v_add_u32_e32 v1, v0, v1
	v_lshlrev_b32_e32 v2, 3, v9
	v_ashrrev_i32_e32 v8, 6, v1
	v_and_b32_e32 v2, -16, v2
	v_add_u32_e32 v2, v8, v2
	v_and_b32_e32 v3, 3, v8
	v_lshrrev_b32_e32 v10, 2, v2
	v_lshlrev_b32_e32 v11, 1, v2
	v_and_b32_e32 v1, 0xc0, v1
	s_ashr_i32 s13, s4, 6
	v_and_or_b32 v3, v2, s0, v3
	v_and_b32_e32 v10, 4, v10
	v_and_b32_e32 v11, 24, v11
	v_sub_u32_e32 v0, v0, v1
	s_ashr_i32 s5, s4, 8
	s_lshl_b32 s17, s13, 10
	v_or3_b32 v3, v3, v10, v11
	v_lshlrev_b32_e32 v10, 5, v9
	v_ashrrev_i16_sdwa v0, v12, sext(v0) dst_sel:DWORD dst_unused:UNUSED_PAD src0_sel:DWORD src1_sel:BYTE_0
	v_readlane_b32 s0, v254, 3
	v_readlane_b32 s6, v254, 54
	v_and_b32_e32 v11, 32, v10
	v_bfe_i32 v10, v0, 0, 16
	v_readlane_b32 s1, v254, 4
	v_readlane_b32 s7, v254, 55
	s_add_u32 s6, s6, s0
	v_add_lshl_u32 v0, v11, v10, 1
	s_addc_u32 s7, s7, s1
	s_add_i32 s18, s17, 0
	v_lshl_add_u32 v132, v3, 11, v0
	s_add_i32 m0, s18, 0x10000
	v_lshl_add_u32 v134, v2, 11, v0
	global_load_lds_dwordx4 v132, s[6:7]
	s_add_i32 m0, s18, 0x12000
	s_add_u32 s0, s6, 0x40000
	global_load_lds_dwordx4 v128, s[6:7]
	s_addc_u32 s1, s7, 0
	s_add_i32 m0, s18, 0x14000
	s_add_i32 s19, s18, 0x2000
	global_load_lds_dwordx4 v132, s[0:1]
	s_add_i32 m0, s18, 0x16000
	s_add_i32 s20, s18, 0x4000
	global_load_lds_dwordx4 v128, s[0:1]
	v_readlane_b32 s0, v254, 10
	s_mov_b32 m0, s18
	v_readlane_b32 s1, v254, 11
	s_add_i32 s21, s18, 0x6000
	v_mov_b32_e32 v133, v181
	v_mov_b32_e32 v129, v181
	s_cmp_eq_u32 s5, 1
	s_mov_b64 s[70:71], s[52:53]
	global_load_lds_dwordx4 v134, s[0:1]
	s_mov_b32 m0, s19
	v_lshl_add_u64 v[0:1], s[6:7], 0, v[132:133]
	global_load_lds_dwordx4 v130, s[0:1]
	v_readlane_b32 s0, v254, 12
	s_mov_b32 m0, s20
	v_readlane_b32 s1, v254, 13
	v_lshl_add_u64 v[2:3], s[6:7], 0, v[128:129]
	s_nop 3
	global_load_lds_dwordx4 v134, s[0:1]
	s_mov_b32 m0, s21
	s_nop 0
	global_load_lds_dwordx4 v130, s[0:1]
	s_cselect_b64 s[0:1], -1, 0
	s_cmp_lg_u32 s5, 1
	s_cbranch_scc1 .LBB0_174
	s_setprio 1
	s_barrier

;     __host__ __device__ bool next(int i, Unit& u) const { const int nr = nwg / G; if (i >= nr) return false; return StaticOrder::next(nr - 1 - i, u); }
; #define PG8_STAGE(bufoff, gbase, voff) do { _Pragma("unroll") for (int _i = 0; _i < 2; ++_i) \
;         __builtin_amdgcn_global_load_lds((const unsigned*)((const char*)(gbase) + (voff)[_i]), (PG8_LAS unsigned*)(lds + (bufoff) + ldsw + _i * 8192), 16, 0, 0); } while (0)
; template <class Epi, class Sched, bool ALIGN_EPI = false, bool SP2 = false>
; __device__ __forceinline__ void gemm_phase(PG8_LAS unsigned char* lds, const Gemm g, const Sched& S, const Epi& E) {
;     ...
;     const int tid = tid_o, wid = __builtin_amdgcn_readfirstlane(tid >> 6), lane = tid & 63, wr = wid >> 2, wc = wid & 3, fr = lane & 15, fq = lane >> 4;
;     const int K = g.K, nt = K / BK;
;     unsigned voffA[2], voffB[2];
; #pragma unroll
;     for (int i = 0; i < 2; ++i) { int R, C; stage_rc(tid * 16 + i * 8192, R, C); const int Rb = Epi::PERM ? ((R & ~31) + perm32(R & 31)) : R;
;         voffA[i] = (unsigned)(R * K + C) * 2u; voffB[i] = (unsigned)(Rb * K + C) * 2u; }
;     const size_t kstep = (size_t)(BK * 2);
;     const size_t hstep = (size_t)HALF * K * 2;
;     const size_t tstep = 2 * hstep;
;     const unsigned ldsw = (unsigned)wid * 1024u;
;     const int aoff = lds_byte(wr * 64 + fr, fq * 8), boff = lds_byte(wc * 32 + fr, fq * 8);
;     ...
;     Unit cur, nxt; int ui = 0;
;     if (!S.next(0, cur)) return;
;     f32x4 acc[2][2][4][2];
; #pragma unroll
;     for (int a = 0; a < 2; ++a)
; #pragma unroll
;         for (int b = 0; b < 2; ++b)
; #pragma unroll
;             for (int m = 0; m < 4; ++m)
; #pragma unroll
;                 for (int n = 0; n < 2; ++n) acc[a][b][m][n] = (f32x4){0.f, 0.f, 0.f, 0.f};
;     bf16x8 At[4][2], B0[2][2], B1[2][2];
;     const char* cA = (const char*)g.A + (size_t)cur.pm * tstep; const char* cB = (const char*)g.Bt + (size_t)cur.pn * tstep;
;     S.a_ready(cur);
;     if constexpr (SP2) {
;         PG8_STAGE(PG8_SB(0, 0), cB, voffB); PG8_STAGE(PG8_SB(0, 1), cB + hstep, voffB); PG8_STAGE(PG8_SA(0, 0), cA, voffA); PG8_STAGE(PG8_SA(0, 1), cA + hstep, voffA);
;         if (wr == 1) PG8_BAR;
;         PG8_WAIT_V(2); PG8_BAR;
;         PG8_STAGE(PG8_SB(1, 0), cB + kstep, voffB); PG8_STAGE(PG8_SA(1, 0), cA + kstep, voffA); PG8_STAGE(PG8_SB(1, 1), cB + hstep + kstep, voffB);
.LBB0_467:
	v_readlane_b32 s4, v253, 50
	s_movk_i32 s0, 0x180
	v_mov_b32_e32 v0, v202
	v_readlane_b32 s5, v253, 51
	s_andn2_b64 vcc, exec, s[4:5]
	v_readfirstlane_b32 s26, v0
	s_cbranch_vccnz .LBB0_489
	v_lshlrev_b32_e32 v4, 4, v0
	v_add_u32_e32 v1, 0x2000, v4
	v_ashrrev_i32_e32 v2, 31, v1
	v_lshrrev_b32_e32 v2, 22, v2
	v_add_u32_e32 v2, v1, v2
	v_ashrrev_i32_e32 v2, 10, v2
	v_mul_i32_i24_e32 v3, 0x400, v2
	v_sub_u32_e32 v1, v1, v3
	v_lshrrev_b32_e32 v3, 4, v1
	v_bitop3_b32 v3, v3, v1, 32 bitop3:0x6c
	v_ashrrev_i32_e32 v1, 31, v3
	v_lshrrev_b32_e32 v1, 26, v1
	v_add_u32_e32 v5, v3, v1
	v_lshlrev_b32_e32 v6, 3, v2
	v_ashrrev_i32_e32 v1, 6, v5
	v_and_b32_e32 v6, -16, v6
	v_add_u32_e32 v6, v1, v6
	v_and_b32_e32 v1, 3, v1
	s_mov_b32 s6, 0x7fffffe0
	v_lshrrev_b32_e32 v7, 2, v6
	v_lshlrev_b32_e32 v8, 1, v6
	v_and_or_b32 v1, v6, s6, v1
	v_and_b32_e32 v7, 4, v7
	v_and_b32_e32 v8, 24, v8
	v_or3_b32 v1, v1, v7, v8
	v_mul_lo_u32 v7, v1, s0
	v_lshlrev_b32_e32 v1, 5, v2
	v_and_b32_e32 v2, 0xc0, v5
	v_sub_u32_e32 v2, v3, v2
	v_mov_b32_e32 v11, 1
	v_ashrrev_i16_sdwa v2, v11, sext(v2) dst_sel:DWORD dst_unused:UNUSED_PAD src0_sel:DWORD src1_sel:BYTE_0
	v_and_b32_e32 v1, 32, v1
	v_bfe_i32 v2, v2, 0, 16
	v_add_u32_e32 v5, v1, v2
	v_mul_lo_u32 v3, v6, s0
	v_add_lshl_u32 v128, v7, v5, 1
	v_add_lshl_u32 v130, v5, v3, 1
	v_bfe_i32 v5, v0, 27, 1
	v_lshrrev_b32_e32 v5, 22, v5
	v_add_u32_e32 v5, v4, v5
	v_and_b32_e32 v5, 0xfffffc00, v5
	v_sub_u32_e32 v4, v4, v5
	v_lshrrev_b32_e32 v5, 4, v4
	v_ashrrev_i32_e32 v7, 31, v0
	v_bitop3_b32 v5, v5, v4, 32 bitop3:0x6c
	v_lshrrev_b32_e32 v7, 26, v7
	v_ashrrev_i32_e32 v4, 31, v5
	v_add_u32_e32 v7, v0, v7
	v_lshrrev_b32_e32 v4, 26, v4
	v_ashrrev_i32_e32 v7, 6, v7
	v_add_u32_e32 v6, v5, v4
	v_lshlrev_b32_e32 v8, 3, v7
	s_add_u32 s13, s70, 0x180000
	v_ashrrev_i32_e32 v4, 6, v6
	v_and_b32_e32 v8, -16, v8
	s_addc_u32 s15, s71, 0
	s_ashr_i32 s1, s0, 31
	v_add_u32_e32 v8, v4, v8
	v_and_b32_e32 v4, 3, v4
	s_lshl_b64 s[28:29], s[0:1], 9
	v_and_or_b32 v4, v8, s6, v4
	v_readlane_b32 s6, v254, 6
	v_readlane_b32 s16, v254, 5
	s_mul_i32 s6, s28, s6
	s_mul_hi_u32 s7, s28, s16
	s_add_i32 s18, s7, s6
	s_lshr_b64 s[6:7], s[0:1], 23
	v_readlane_b32 s22, v254, 0
	v_lshrrev_b32_e32 v9, 2, v8
	v_lshlrev_b32_e32 v10, 1, v8
	s_mul_i32 s7, s6, s16
	v_readlane_b32 s23, v254, 1
	v_and_b32_e32 v9, 4, v9
	v_and_b32_e32 v10, 24, v10
	v_and_b32_e32 v6, 0xc0, v6
	s_add_i32 s7, s18, s7
	s_mul_i32 s18, s28, s23
	s_mul_hi_u32 s20, s28, s22
	s_ashr_i32 s24, s26, 6
	v_or3_b32 v4, v4, v9, v10
	v_sub_u32_e32 v5, v5, v6
	s_add_i32 s18, s20, s18
	s_mul_i32 s6, s6, s22
	s_ashr_i32 s25, s26, 8
	s_lshl_b64 s[4:5], s[0:1], 8
	s_lshl_b32 s17, s24, 10
	v_mul_lo_u32 v9, v4, s0
	v_lshlrev_b32_e32 v4, 5, v7
	v_ashrrev_i16_sdwa v5, v11, sext(v5) dst_sel:DWORD dst_unused:UNUSED_PAD src0_sel:DWORD src1_sel:BYTE_0
	s_add_i32 s18, s18, s6
	s_mul_i32 s6, s28, s22
	v_and_b32_e32 v4, 32, v4
	v_bfe_i32 v5, v5, 0, 16
	s_add_u32 s46, s13, s6
	v_add_u32_e32 v7, v4, v5
	s_addc_u32 s47, s15, s18
	s_add_i32 s18, s17, 0
	v_add_lshl_u32 v132, v9, v7, 1
	s_add_i32 m0, s18, 0x10000
	s_mul_i32 s19, s28, s16
	global_load_lds_dwordx4 v132, s[46:47]
	s_add_i32 m0, s18, 0x12000
	s_add_u32 s38, s46, s4
	global_load_lds_dwordx4 v128, s[46:47]
	s_addc_u32 s39, s47, s5
	s_add_i32 m0, s18, 0x14000
	v_mul_lo_u32 v6, v8, s0
	global_load_lds_dwordx4 v132, s[38:39]
	s_add_i32 m0, s18, 0x16000
	s_add_u32 s6, s62, s19
	s_addc_u32 s7, s63, s7
	s_add_i32 s19, s18, 0x2000
	v_add_lshl_u32 v134, v7, v6, 1
	global_load_lds_dwordx4 v128, s[38:39]
	s_mov_b32 m0, s18
	s_add_u32 s22, s6, s4
	global_load_lds_dwordx4 v134, s[6:7]
	s_mov_b32 m0, s19
	s_addc_u32 s23, s7, s5
	s_add_i32 s20, s18, 0x4000
	global_load_lds_dwordx4 v130, s[6:7]
	s_mov_b32 m0, s20
	s_add_i32 s21, s18, 0x6000
	global_load_lds_dwordx4 v134, s[22:23]
	s_mov_b32 m0, s21
	s_cmp_eq_u32 s25, 1
	global_load_lds_dwordx4 v130, s[22:23]
	s_mov_b64 s[72:73], s[52:53]
	s_cselect_b64 s[30:31], -1, 0
	s_cmp_lg_u32 s25, 1
	s_movk_i32 s16, 0x61
	s_cbranch_scc1 .LBB0_470
	s_setprio 1
	s_barrier

;     __host__ __device__ bool next(int i, Unit& u) const { const int nr = nwg / G; if (i >= nr) return false; return StaticOrder::next(nr - 1 - i, u); }
; #define PG8_STAGE(bufoff, gbase, voff) do { _Pragma("unroll") for (int _i = 0; _i < 2; ++_i) \
;         __builtin_amdgcn_global_load_lds((const unsigned*)((const char*)(gbase) + (voff)[_i]), (PG8_LAS unsigned*)(lds + (bufoff) + ldsw + _i * 8192), 16, 0, 0); } while (0)
; template <class Epi, class Sched, bool ALIGN_EPI = false, bool SP2 = false>
; __device__ __forceinline__ void gemm_phase(PG8_LAS unsigned char* lds, const Gemm g, const Sched& S, const Epi& E) {
;     ...
;     const int tid = tid_o, wid = __builtin_amdgcn_readfirstlane(tid >> 6), lane = tid & 63, wr = wid >> 2, wc = wid & 3, fr = lane & 15, fq = lane >> 4;
;     const int K = g.K, nt = K / BK;
;     unsigned voffA[2], voffB[2];
; #pragma unroll
;     for (int i = 0; i < 2; ++i) { int R, C; stage_rc(tid * 16 + i * 8192, R, C); const int Rb = Epi::PERM ? ((R & ~31) + perm32(R & 31)) : R;
;         voffA[i] = (unsigned)(R * K + C) * 2u; voffB[i] = (unsigned)(Rb * K + C) * 2u; }
;     const size_t kstep = (size_t)(BK * 2);
;     const size_t hstep = (size_t)HALF * K * 2;
;     const size_t tstep = 2 * hstep;
;     const unsigned ldsw = (unsigned)wid * 1024u;
;     const int aoff = lds_byte(wr * 64 + fr, fq * 8), boff = lds_byte(wc * 32 + fr, fq * 8);
;     ...
;     Unit cur, nxt; int ui = 0;
;     if (!S.next(0, cur)) return;
;     f32x4 acc[2][2][4][2];
; #pragma unroll
;     for (int a = 0; a < 2; ++a)
; #pragma unroll
;         for (int b = 0; b < 2; ++b)
; #pragma unroll
;             for (int m = 0; m < 4; ++m)
; #pragma unroll
;                 for (int n = 0; n < 2; ++n) acc[a][b][m][n] = (f32x4){0.f, 0.f, 0.f, 0.f};
;     bf16x8 At[4][2], B0[2][2], B1[2][2];
;     const char* cA = (const char*)g.A + (size_t)cur.pm * tstep; const char* cB = (const char*)g.Bt + (size_t)cur.pn * tstep;
;     S.a_ready(cur);
;     if constexpr (SP2) {
;         PG8_STAGE(PG8_SB(0, 0), cB, voffB); PG8_STAGE(PG8_SB(0, 1), cB + hstep, voffB); PG8_STAGE(PG8_SA(0, 0), cA, voffA); PG8_STAGE(PG8_SA(0, 1), cA + hstep, voffA);
;         if (wr == 1) PG8_BAR;
;         PG8_WAIT_V(2); PG8_BAR;
;         PG8_STAGE(PG8_SB(1, 0), cB + kstep, voffB); PG8_STAGE(PG8_SA(1, 0), cA + kstep, voffA); PG8_STAGE(PG8_SB(1, 1), cB + hstep + kstep, voffB);
.LBB0_492:
	s_lshl_b32 s6, s63, 7
	s_mov_b32 s7, s51
	s_andn2_b64 vcc, exec, s[4:5]
	v_writelane_b32 v255, s6, 0
	s_nop 1
	v_writelane_b32 v255, s7, 1
	s_cbranch_vccnz .LBB0_698
	v_bfe_i32 v2, v12, 27, 1
	v_lshlrev_b32_e32 v0, 4, v12
	v_lshrrev_b32_e32 v2, 22, v2
	v_add_u32_e32 v2, v0, v2
	v_and_b32_e32 v2, 0xfffffc00, v2
	v_sub_u32_e32 v2, v0, v2
	s_waitcnt lgkmcnt(0)
	v_ashrrev_i32_e32 v1, 31, v12
	v_lshrrev_b32_e32 v3, 4, v2
	v_lshrrev_b32_e32 v1, 26, v1
	v_bitop3_b32 v2, v3, v2, 32 bitop3:0x6c
	v_add_u32_e32 v1, v12, v1
	v_ashrrev_i32_e32 v4, 31, v2
	v_ashrrev_i32_e32 v1, 6, v1
	v_lshrrev_b32_e32 v4, 26, v4
	v_lshlrev_b32_e32 v3, 3, v1
	v_add_u32_e32 v4, v2, v4
	v_and_b32_e32 v3, -16, v3
	v_ashrrev_i32_e32 v5, 6, v4
	v_lshlrev_b32_e32 v1, 5, v1
	v_add_u32_e32 v3, v5, v3
	v_and_b32_e32 v13, 32, v1
	v_and_b32_e32 v1, 0xc0, v4
	v_sub_u32_e32 v1, v2, v1
	v_mov_b32_e32 v6, 1
	v_lshlrev_b32_e32 v2, 1, v3
	v_lshrrev_b32_e32 v4, 2, v3
	v_and_b32_e32 v5, 3, v5
	s_mov_b32 s4, 0x7fffffe0
	v_ashrrev_i16_sdwa v1, v6, sext(v1) dst_sel:DWORD dst_unused:UNUSED_PAD src0_sel:DWORD src1_sel:BYTE_0
	v_and_b32_e32 v2, 24, v2
	v_and_b32_e32 v4, 4, v4
	v_and_or_b32 v5, v3, s4, v5
	v_bfe_i32 v14, v1, 0, 16
	v_or3_b32 v2, v5, v4, v2
	v_add_u32_e32 v1, v13, v14
	v_mul_lo_u32 v15, v3, s34
	v_mul_lo_u32 v2, v2, s34
	v_add_u32_e32 v0, 0x2000, v0
	v_add_lshl_u32 v128, v1, v15, 1
	v_add_lshl_u32 v130, v2, v1, 1
	v_ashrrev_i32_e32 v1, 31, v0
	v_lshrrev_b32_e32 v1, 22, v1
	v_add_u32_e32 v1, v0, v1
	v_ashrrev_i32_e32 v1, 10, v1
	v_mul_i32_i24_e32 v2, 0x400, v1
	v_sub_u32_e32 v0, v0, v2
	v_lshrrev_b32_e32 v2, 4, v0
	v_bitop3_b32 v0, v2, v0, 32 bitop3:0x6c
	v_ashrrev_i32_e32 v3, 31, v0
	v_lshrrev_b32_e32 v3, 26, v3
	v_lshlrev_b32_e32 v2, 3, v1
	v_add_u32_e32 v3, v0, v3
	s_ashr_i32 s21, s15, 6
	v_and_b32_e32 v2, -16, v2
	v_ashrrev_i32_e32 v4, 6, v3
	v_lshlrev_b32_e32 v1, 5, v1
	s_lshl_b32 s18, s34, 9
	v_add_u32_e32 v2, v4, v2
	v_and_b32_e32 v16, 32, v1
	v_and_b32_e32 v1, 0xc0, v3
	v_and_b32_e32 v4, 3, v4
	s_ashr_i32 s22, s15, 8
	s_lshl_b32 s40, s34, 8
	s_lshl_b32 s19, s21, 10
	s_mul_i32 s5, s18, s25
	v_readlane_b32 s6, v254, 56
	v_sub_u32_e32 v0, v0, v1
	v_lshlrev_b32_e32 v1, 1, v2
	v_lshrrev_b32_e32 v3, 2, v2
	v_and_or_b32 v4, v2, s4, v4
	s_mul_hi_i32 s4, s18, s25
	v_readlane_b32 s7, v254, 57
	s_add_u32 s6, s6, s5
	v_ashrrev_i16_sdwa v0, v6, sext(v0) dst_sel:DWORD dst_unused:UNUSED_PAD src0_sel:DWORD src1_sel:BYTE_0
	v_and_b32_e32 v1, 24, v1
	v_and_b32_e32 v3, 4, v3
	s_addc_u32 s7, s7, s4
	s_add_i32 s75, s19, 0
	v_bfe_i32 v17, v0, 0, 16
	v_or3_b32 v1, v4, v3, v1
	s_add_i32 m0, s75, 0x10000
	v_add_u32_e32 v0, v16, v17
	v_mul_lo_u32 v1, v1, s34
	global_load_lds_dwordx4 v130, s[6:7]
	s_add_i32 m0, s75, 0x12000
	v_add_lshl_u32 v134, v1, v0, 1
	s_add_u32 s4, s6, s40
	global_load_lds_dwordx4 v134, s[6:7]
	s_addc_u32 s5, s7, 0
	s_add_i32 m0, s75, 0x14000
	v_mov_b32_e32 v131, v181
	v_mov_b32_e32 v135, v181
	global_load_lds_dwordx4 v130, s[4:5]
	s_add_i32 m0, s75, 0x16000
	s_mul_i32 s24, s18, s1
	v_lshl_add_u64 v[4:5], s[4:5], 0, v[130:131]
	v_lshl_add_u64 v[6:7], s[4:5], 0, v[134:135]
	global_load_lds_dwordx4 v134, s[4:5]
	v_readlane_b32 s4, v254, 58
	s_mul_hi_i32 s23, s18, s1
	v_readlane_b32 s5, v254, 59
	s_add_u32 s4, s4, s24
	s_addc_u32 s5, s5, s23
	s_add_i32 s76, s75, 0x2000
	v_mul_lo_u32 v18, v2, s34
	s_mov_b32 m0, s75
	s_add_u32 s26, s4, s40
	v_add_lshl_u32 v132, v0, v18, 1
	global_load_lds_dwordx4 v128, s[4:5]
	s_mov_b32 m0, s76
	s_addc_u32 s27, s5, 0
	s_add_i32 s77, s75, 0x4000
	global_load_lds_dwordx4 v132, s[4:5]
	s_mov_b32 m0, s77
	s_add_i32 s78, s75, 0x6000
	global_load_lds_dwordx4 v128, s[26:27]
	s_mov_b32 m0, s78
	s_cmp_eq_u32 s22, 1
	global_load_lds_dwordx4 v132, s[26:27]
	s_cselect_b64 s[16:17], -1, 0
	v_mov_b32_e32 v129, v181
	v_mov_b32_e32 v133, v181
	v_writelane_b32 v255, s16, 2
	s_mov_b32 s41, s51
	v_lshl_add_u64 v[0:1], s[6:7], 0, v[130:131]
	v_lshl_add_u64 v[2:3], s[6:7], 0, v[134:135]
	v_lshl_add_u64 v[8:9], s[4:5], 0, v[128:129]
	v_lshl_add_u64 v[10:11], s[4:5], 0, v[132:133]
	v_writelane_b32 v255, s17, 3
	s_cmp_lg_u32 s22, 1
	s_cbranch_scc1 .LBB0_495
	s_setprio 1
	s_barrier

; template <int DQK, bool MOBA>
; __device__ __forceinline__ void attn_phase(const Args& A, lptr lds, int vcu, int G) {
;     ...
;         for (int r = 0; r < 4; ++r) {
;             const int bh = x * 16 + r * 4 + gq;
;             const int k2 = (k + 4) & 7;
;             const int qb = (r == 0) ? k : (r == 1) ? 7 - k : (r == 2) ? k2 : 7 - k2;
;             attn_unit<DQK, MOBA>(A, bh / NH, bh % NH, qb, lds);
.LBB0_756:
	s_setprio 0
	s_cmp_lt_i32 s53, 1
	s_mov_b32 s18, s49
	s_cbranch_scc1 .LBB0_761
	s_cmp_lg_u32 s53, 1
	s_mov_b64 s[0:1], -1
	s_cbranch_scc0 .LBB0_759
	s_cmp_eq_u32 s53, 2
	s_cselect_b32 s0, 4, 3
	s_xor_b32 s18, s0, s49
	s_mov_b64 s[0:1], 0

; template <int DQK, bool MOBA>
; __device__ __forceinline__ void attn_phase(const Args& A, lptr lds, int vcu, int G) {
;     ...
;         for (int r = 0; r < 4; ++r) {
;             const int bh = x * 16 + r * 4 + gq;
;             const int k2 = (k + 4) & 7;
;             const int qb = (r == 0) ? k : (r == 1) ? 7 - k : (r == 2) ? k2 : 7 - k2;
;             attn_unit<DQK, MOBA>(A, bh / NH, bh % NH, qb, lds);
.LBB0_804:
	s_setprio 0
	s_cmp_lt_i32 s21, 1
	s_mov_b32 s22, s18
	s_cbranch_scc1 .LBB0_809
	s_cmp_lg_u32 s21, 1
	s_mov_b64 s[0:1], -1
	s_cbranch_scc0 .LBB0_807
	s_cmp_eq_u32 s21, 2
	s_cselect_b32 s0, 4, 3
	s_xor_b32 s22, s0, s18
	s_mov_b64 s[0:1], 0

;     __host__ __device__ bool next(int i, Unit& u) const { const int nr = nwg / G; if (i >= nr) return false; return StaticOrder::next(nr - 1 - i, u); }
; #define PG8_STAGE(bufoff, gbase, voff) do { _Pragma("unroll") for (int _i = 0; _i < 2; ++_i) \
;         __builtin_amdgcn_global_load_lds((const unsigned*)((const char*)(gbase) + (voff)[_i]), (PG8_LAS unsigned*)(lds + (bufoff) + ldsw + _i * 8192), 16, 0, 0); } while (0)
; template <class Epi, class Sched, bool ALIGN_EPI = false, bool SP2 = false>
; __device__ __forceinline__ void gemm_phase(PG8_LAS unsigned char* lds, const Gemm g, const Sched& S, const Epi& E) {
;     ...
;     const int tid = tid_o, wid = __builtin_amdgcn_readfirstlane(tid >> 6), lane = tid & 63, wr = wid >> 2, wc = wid & 3, fr = lane & 15, fq = lane >> 4;
;     const int K = g.K, nt = K / BK;
;     unsigned voffA[2], voffB[2];
; #pragma unroll
;     for (int i = 0; i < 2; ++i) { int R, C; stage_rc(tid * 16 + i * 8192, R, C); const int Rb = Epi::PERM ? ((R & ~31) + perm32(R & 31)) : R;
;         voffA[i] = (unsigned)(R * K + C) * 2u; voffB[i] = (unsigned)(Rb * K + C) * 2u; }
;     const size_t kstep = (size_t)(BK * 2);
;     const size_t hstep = (size_t)HALF * K * 2;
;     const size_t tstep = 2 * hstep;
;     const unsigned ldsw = (unsigned)wid * 1024u;
;     const int aoff = lds_byte(wr * 64 + fr, fq * 8), boff = lds_byte(wc * 32 + fr, fq * 8);
;     ...
;     Unit cur, nxt; int ui = 0;
;     if (!S.next(0, cur)) return;
;     f32x4 acc[2][2][4][2];
; #pragma unroll
;     for (int a = 0; a < 2; ++a)
; #pragma unroll
;         for (int b = 0; b < 2; ++b)
; #pragma unroll
;             for (int m = 0; m < 4; ++m)
; #pragma unroll
;                 for (int n = 0; n < 2; ++n) acc[a][b][m][n] = (f32x4){0.f, 0.f, 0.f, 0.f};
;     bf16x8 At[4][2], B0[2][2], B1[2][2];
;     const char* cA = (const char*)g.A + (size_t)cur.pm * tstep; const char* cB = (const char*)g.Bt + (size_t)cur.pn * tstep;
;     S.a_ready(cur);
;     if constexpr (SP2) {
;         PG8_STAGE(PG8_SB(0, 0), cB, voffB); PG8_STAGE(PG8_SB(0, 1), cB + hstep, voffB); PG8_STAGE(PG8_SA(0, 0), cA, voffA); PG8_STAGE(PG8_SA(0, 1), cA + hstep, voffA);
;         if (wr == 1) PG8_BAR;
;         PG8_WAIT_V(2); PG8_BAR;
;         PG8_STAGE(PG8_SB(1, 0), cB + kstep, voffB); PG8_STAGE(PG8_SA(1, 0), cA + kstep, voffA); PG8_STAGE(PG8_SB(1, 1), cB + hstep + kstep, voffB);
.LBB0_877:
	v_readlane_b32 s0, v253, 60
	v_mov_b32_e32 v12, v202
	v_readlane_b32 s1, v253, 61
	s_andn2_b64 vcc, exec, s[0:1]
	v_readfirstlane_b32 s0, v12
	s_cbranch_vccnz .LBB0_996
	v_lshlrev_b32_e32 v0, 4, v12
	s_waitcnt lgkmcnt(0)
	v_add_u32_e32 v1, 0x2000, v0
	v_ashrrev_i32_e32 v2, 31, v1
	v_lshrrev_b32_e32 v2, 22, v2
	v_add_u32_e32 v2, v1, v2
	v_ashrrev_i32_e32 v2, 10, v2
	v_mul_i32_i24_e32 v3, 0x400, v2
	v_sub_u32_e32 v1, v1, v3
	v_lshrrev_b32_e32 v3, 4, v1
	v_bitop3_b32 v1, v3, v1, 32 bitop3:0x6c
	s_and_b64 s[4:5], s[28:29], exec
	v_ashrrev_i32_e32 v3, 31, v1
	v_readlane_b32 s4, v254, 62
	v_lshrrev_b32_e32 v3, 26, v3
	s_cselect_b32 s21, s4, s88
	v_readlane_b32 s1, v255, 13
	v_readlane_b32 s4, v254, 58
	v_add_u32_e32 v3, v1, v3
	v_lshlrev_b32_e32 v5, 3, v2
	s_cselect_b32 s22, s1, s4
	v_readlane_b32 s1, v255, 4
	v_readlane_b32 s4, v254, 54
	v_ashrrev_i32_e32 v4, 6, v3
	v_and_b32_e32 v5, -16, v5
	v_readlane_b32 s5, v254, 63
	s_cselect_b32 s23, s1, s4
	s_movk_i32 s1, 0x400
	v_add_u32_e32 v5, v4, v5
	s_cselect_b32 s20, s5, s89
	s_cselect_b32 s1, s1, 0x1000
	s_ashr_i32 s5, s0, 6
	v_and_b32_e32 v4, 3, v4
	s_mov_b32 s13, 0x7fffffe0
	v_lshrrev_b32_e32 v6, 2, v5
	v_lshlrev_b32_e32 v7, 1, v5
	s_ashr_i32 s4, s0, 8
	s_lshl_b32 s48, s1, 8
	s_lshl_b32 s24, s5, 10
	v_and_or_b32 v4, v5, s13, v4
	v_and_b32_e32 v6, 4, v6
	v_and_b32_e32 v7, 24, v7
	v_and_b32_e32 v3, 0xc0, v3
	v_or3_b32 v4, v4, v6, v7
	s_and_b64 s[6:7], s[28:29], exec
	v_lshlrev_b32_e32 v2, 5, v2
	v_sub_u32_e32 v1, v1, v3
	v_mov_b32_e32 v7, 1
	s_cselect_b32 s6, 10, 12
	v_and_b32_e32 v2, 32, v2
	v_ashrrev_i16_sdwa v1, v7, sext(v1) dst_sel:DWORD dst_unused:UNUSED_PAD src0_sel:DWORD src1_sel:BYTE_0
	v_lshlrev_b32_e32 v4, s6, v4
	v_add_u32_sdwa v1, v2, sext(v1) dst_sel:DWORD dst_unused:UNUSED_PAD src0_sel:DWORD src1_sel:WORD_0
	v_lshlrev_b32_e32 v2, s6, v5
	s_waitcnt vmcnt(16)
	v_add_lshl_u32 v160, v4, v1, 1
	v_add_lshl_u32 v162, v1, v2, 1
	v_bfe_i32 v1, v12, 27, 1
	v_lshrrev_b32_e32 v1, 22, v1
	v_add_u32_e32 v1, v0, v1
	v_and_b32_e32 v1, 0xfffffc00, v1
	v_sub_u32_e32 v0, v0, v1
	v_lshrrev_b32_e32 v1, 4, v0
	v_ashrrev_i32_e32 v3, 31, v12
	v_bitop3_b32 v0, v1, v0, 32 bitop3:0x6c
	v_lshrrev_b32_e32 v3, 26, v3
	v_ashrrev_i32_e32 v1, 31, v0
	v_add_u32_e32 v3, v12, v3
	v_lshrrev_b32_e32 v1, 26, v1
	v_ashrrev_i32_e32 v3, 6, v3
	v_add_u32_e32 v1, v0, v1
	v_lshlrev_b32_e32 v4, 3, v3
	v_ashrrev_i32_e32 v2, 6, v1
	v_and_b32_e32 v4, -16, v4
	v_add_u32_e32 v4, v2, v4
	v_and_b32_e32 v2, 3, v2
	v_lshrrev_b32_e32 v5, 2, v4
	v_lshlrev_b32_e32 v6, 1, v4
	v_and_or_b32 v2, v4, s13, v2
	v_and_b32_e32 v5, 4, v5
	v_and_b32_e32 v6, 24, v6
	v_or3_b32 v2, v2, v5, v6
	v_and_b32_e32 v1, 0xc0, v1
	v_lshlrev_b32_e32 v2, s6, v2
	v_sub_u32_e32 v0, v0, v1
	v_lshlrev_b32_e32 v1, s6, v4
	v_readlane_b32 s6, v254, 14
	v_readlane_b32 s26, v254, 16
	s_cselect_b32 s25, 19, 21
	v_readlane_b32 s7, v254, 15
	v_readlane_b32 s27, v254, 17
	v_lshlrev_b32_e32 v3, 5, v3
	s_lshl_b64 s[6:7], s[6:7], s25
	s_lshl_b64 s[26:27], s[26:27], s25
	v_and_b32_e32 v3, 32, v3
	v_ashrrev_i16_sdwa v0, v7, sext(v0) dst_sel:DWORD dst_unused:UNUSED_PAD src0_sel:DWORD src1_sel:BYTE_0
	s_add_u32 s42, s23, s26
	v_add_u32_sdwa v0, v3, sext(v0) dst_sel:DWORD dst_unused:UNUSED_PAD src0_sel:DWORD src1_sel:WORD_0
	s_addc_u32 s43, s22, s27
	s_add_i32 s19, s24, 0
	v_add_lshl_u32 v180, v2, v0, 1
	s_add_i32 m0, s19, 0x10000
	s_mov_b32 s36, s85
	global_load_lds_dwordx4 v180, s[42:43]
	s_add_i32 m0, s19, 0x12000
	s_add_u32 s26, s42, s48
	global_load_lds_dwordx4 v160, s[42:43]
	s_addc_u32 s27, s43, 0
	s_add_i32 m0, s19, 0x14000
	v_mov_b32_e32 v161, v181
	global_load_lds_dwordx4 v180, s[26:27]
	s_add_i32 m0, s19, 0x16000
	s_add_u32 s6, s21, s6
	s_addc_u32 s7, s20, s7
	s_add_i32 s85, s19, 0x2000
	v_add_lshl_u32 v164, v0, v1, 1
	v_lshl_add_u64 v[4:5], s[26:27], 0, v[180:181]
	v_lshl_add_u64 v[6:7], s[26:27], 0, v[160:161]
	global_load_lds_dwordx4 v160, s[26:27]
	s_mov_b32 m0, s19
	s_add_u32 s26, s6, s48
	global_load_lds_dwordx4 v164, s[6:7]
	s_mov_b32 m0, s85
	s_addc_u32 s27, s7, 0
	s_add_i32 s64, s19, 0x4000
	global_load_lds_dwordx4 v162, s[6:7]
	s_mov_b32 m0, s64
	s_add_i32 s65, s19, 0x6000
	global_load_lds_dwordx4 v164, s[26:27]
	s_mov_b32 m0, s65
	v_mov_b32_e32 v165, v181
	global_load_lds_dwordx4 v162, s[26:27]
	v_mov_b32_e32 v163, v181
	s_cmp_eq_u32 s4, 1
	s_mov_b32 s49, s51
	v_lshl_add_u64 v[0:1], s[42:43], 0, v[180:181]
	v_lshl_add_u64 v[2:3], s[42:43], 0, v[160:161]
	v_lshl_add_u64 v[8:9], s[6:7], 0, v[164:165]
	v_lshl_add_u64 v[10:11], s[6:7], 0, v[162:163]
	s_cselect_b64 s[70:71], -1, 0
	s_cmp_lg_u32 s4, 1
	s_cbranch_scc1 .LBB0_880
	s_setprio 1
	s_barrier

;     __host__ __device__ bool next(int i, Unit& u) const { const int nr = nwg / G; if (i >= nr) return false; return StaticOrder::next(nr - 1 - i, u); }
; #define PG8_BAR __builtin_amdgcn_s_barrier()
;     __host__ __device__ bool next(int i, Unit& u) const {
;         const long L = (long)i * G + c; if (L >= nwg) return false;
;         int wgid = (int)L; { const int q = nwg / NXCD, r = nwg % NXCD, xcd = wgid % NXCD, off = wgid / NXCD; wgid = (xcd < r ? xcd * (q + 1) : r * (q + 1) + (xcd - r) * q) + off; }
;         const int nig = WGM * nN, gid = wgid / nig, fm = gid * WGM, gsz = (nM - fm) < WGM ? (nM - fm) : WGM;
;         u.pm = fm + ((wgid % nig) % gsz); u.pn = (wgid % nig) / gsz; return true;
; template <class Epi, class Sched, bool ALIGN_EPI = false, bool SP2 = false>
; __device__ __forceinline__ void gemm_phase(PG8_LAS unsigned char* lds, const Gemm g, const Sched& S, const Epi& E) {
;     ...
;     for (int i = 0; i < 2; ++i) { int R, C; stage_rc(tid * 16 + i * 8192, R, C); const int Rb = Epi::PERM ? ((R & ~31) + perm32(R & 31)) : R;
;         voffA[i] = (unsigned)(R * K + C) * 2u; voffB[i] = (unsigned)(Rb * K + C) * 2u; }
;     const size_t kstep = (size_t)(BK * 2);
;     const size_t hstep = (size_t)HALF * K * 2;
;     const size_t tstep = 2 * hstep;
;     const unsigned ldsw = (unsigned)wid * 1024u;
;     const int aoff = lds_byte(wr * 64 + fr, fq * 8), boff = lds_byte(wc * 32 + fr, fq * 8);
;     ...
;     Unit cur, nxt; int ui = 0;
;     if (!S.next(0, cur)) return;
;     f32x4 acc[2][2][4][2];
; #pragma unroll
;     for (int a = 0; a < 2; ++a)
; #pragma unroll
;         for (int b = 0; b < 2; ++b)
; #pragma unroll
;             for (int m = 0; m < 4; ++m)
; #pragma unroll
;                 for (int n = 0; n < 2; ++n) acc[a][b][m][n] = (f32x4){0.f, 0.f, 0.f, 0.f};
;     bf16x8 At[4][2], B0[2][2], B1[2][2];
;     const char* cA = (const char*)g.A + (size_t)cur.pm * tstep; const char* cB = (const char*)g.Bt + (size_t)cur.pn * tstep;
;     S.a_ready(cur);
;     if constexpr (SP2) {
;         PG8_STAGE(PG8_SB(0, 0), cB, voffB); PG8_STAGE(PG8_SB(0, 1), cB + hstep, voffB); PG8_STAGE(PG8_SA(0, 0), cA, voffA); PG8_STAGE(PG8_SA(0, 1), cA + hstep, voffA);
;         if (wr == 1) PG8_BAR;
;         PG8_WAIT_V(2); PG8_BAR;
;         PG8_STAGE(PG8_SB(1, 0), cB + kstep, voffB); PG8_STAGE(PG8_SA(1, 0), cA + kstep, voffA); PG8_STAGE(PG8_SB(1, 1), cB + hstep + kstep, voffB);
.LBB0_1054:
	v_bfe_i32 v1, v6, 27, 1
	v_lshlrev_b32_e32 v3, 4, v6
	v_lshrrev_b32_e32 v1, 22, v1
	v_ashrrev_i32_e32 v0, 31, v6
	v_add_u32_e32 v1, v3, v1
	v_lshrrev_b32_e32 v0, 26, v0
	v_and_b32_e32 v1, 0xfffffc00, v1
	v_add_u32_e32 v0, v6, v0
	v_sub_u32_e32 v1, v3, v1
	v_ashrrev_i32_e32 v0, 6, v0
	v_lshrrev_b32_e32 v2, 4, v1
	v_bitop3_b32 v2, v2, v1, 32 bitop3:0x6c
	v_lshlrev_b32_e32 v1, 3, v0
	v_and_b32_e32 v4, -16, v1
	v_ashrrev_i32_e32 v1, 31, v2
	v_lshrrev_b32_e32 v1, 26, v1
	v_add_u32_e32 v5, v2, v1
	v_ashrrev_i32_e32 v1, 6, v5
	v_and_b32_e32 v5, 0xc0, v5
	v_sub_u32_e32 v2, v2, v5
	v_mov_b32_e32 v10, 1
	v_lshlrev_b32_e32 v7, 5, v0
	v_ashrrev_i16_sdwa v2, v10, sext(v2) dst_sel:DWORD dst_unused:UNUSED_PAD src0_sel:DWORD src1_sel:BYTE_0
	v_and_b32_e32 v7, 32, v7
	v_bfe_i32 v2, v2, 0, 16
	v_add_u32_e32 v4, v1, v4
	v_and_b32_e32 v9, 3, v1
	s_mov_b32 s1, 0x1fffe0
	v_add_lshl_u32 v7, v7, v2, 1
	v_lshlrev_b32_e32 v5, 1, v4
	v_lshrrev_b32_e32 v8, 2, v4
	v_and_or_b32 v9, v4, s1, v9
	v_lshl_add_u32 v128, v4, 11, v7
	v_add_u32_e32 v4, 0x2000, v3
	v_ashrrev_i32_e32 v3, 31, v4
	v_lshrrev_b32_e32 v3, 22, v3
	v_and_b32_e32 v5, 24, v5
	v_and_b32_e32 v8, 4, v8
	v_add_u32_e32 v3, v4, v3
	v_or3_b32 v5, v9, v8, v5
	v_ashrrev_i32_e32 v3, 10, v3
	v_lshl_add_u32 v130, v5, 11, v7
	v_mul_i32_i24_e32 v5, 0x400, v3
	v_sub_u32_e32 v4, v4, v5
	v_lshrrev_b32_e32 v5, 4, v4
	v_bitop3_b32 v5, v5, v4, 32 bitop3:0x6c
	v_lshlrev_b32_e32 v4, 3, v3
	v_and_b32_e32 v7, -16, v4
	v_ashrrev_i32_e32 v4, 31, v5
	v_lshrrev_b32_e32 v4, 26, v4
	v_add_u32_e32 v8, v5, v4
	v_ashrrev_i32_e32 v4, 6, v8
	v_add_u32_e32 v7, v4, v7
	v_and_b32_e32 v11, 3, v4
	v_and_or_b32 v11, v7, s1, v11
	v_readlane_b32 s1, v254, 22
	s_add_i32 s0, s0, s1
	s_ashr_i32 s1, s0, 31
	s_lshr_b32 s1, s1, 25
	s_add_i32 s1, s0, s1
	v_and_b32_e32 v8, 0xc0, v8
	s_ashr_i32 s6, s1, 7
	v_sub_u32_e32 v5, v5, v8
	s_lshl_b32 s6, s6, 3
	v_lshlrev_b32_e32 v9, 5, v3
	v_ashrrev_i16_sdwa v5, v10, sext(v5) dst_sel:DWORD dst_unused:UNUSED_PAD src0_sel:DWORD src1_sel:BYTE_0
	s_sub_i32 s7, 0x80, s6
	v_and_b32_e32 v9, 32, v9
	v_bfe_i32 v5, v5, 0, 16
	s_min_i32 s7, s7, 8
	v_add_lshl_u32 v9, v9, v5, 1
	s_abs_i32 s15, s7
	v_lshlrev_b32_e32 v8, 1, v7
	v_lshrrev_b32_e32 v10, 2, v7
	v_lshl_add_u32 v132, v7, 11, v9
	v_cvt_f32_u32_e32 v7, s15
	s_sub_i32 s19, 0, s15
	s_and_b32 s1, s1, 0xffffff80
	s_sub_i32 s0, s0, s1
	v_rcp_iflag_f32_e32 v7, v7
	s_abs_i32 s16, s0
	s_ashr_i32 s5, s4, 6
	s_xor_b32 s1, s0, s7
	v_mul_f32_e32 v7, 0x4f7ffffe, v7
	v_cvt_u32_f32_e32 v7, v7
	s_ashr_i32 s22, s4, 8
	s_lshl_b32 s13, s5, 10
	s_ashr_i32 s1, s1, 31
	v_readfirstlane_b32 s20, v7
	s_mul_i32 s19, s19, s20
	s_mul_hi_u32 s19, s20, s19
	s_add_i32 s20, s20, s19
	s_mul_hi_u32 s19, s16, s20
	s_mul_i32 s20, s19, s15
	s_sub_i32 s16, s16, s20
	s_add_i32 s20, s19, 1
	s_sub_i32 s21, s16, s15
	s_cmp_ge_u32 s16, s15
	s_cselect_b32 s19, s20, s19
	s_cselect_b32 s16, s21, s16
	s_add_i32 s20, s19, 1
	s_cmp_ge_u32 s16, s15
	s_cselect_b32 s15, s20, s19
	s_xor_b32 s15, s15, s1
	s_sub_i32 s44, s15, s1
	s_mul_i32 s1, s44, s7
	s_sub_i32 s0, s0, s1
	s_add_i32 s46, s6, s0
	s_ashr_i32 s47, s46, 31
	s_ashr_i32 s45, s44, 31
	s_lshl_b64 s[0:1], s[46:47], 19
	s_lshl_b64 s[6:7], s[44:45], 19
	s_add_u32 s48, s17, s6
	s_addc_u32 s49, s18, s7
	s_add_i32 s15, s13, 0
	v_and_b32_e32 v8, 24, v8
	v_and_b32_e32 v10, 4, v10
	s_add_i32 m0, s15, 0x10000
	v_or3_b32 v8, v11, v10, v8
	global_load_lds_dwordx4 v130, s[48:49]
	s_add_i32 m0, s15, 0x12000
	v_lshl_add_u32 v134, v8, 11, v9
	s_add_u32 s6, s48, 0x40000
	global_load_lds_dwordx4 v134, s[48:49]
	s_addc_u32 s7, s49, 0
	s_add_i32 m0, s15, 0x14000
	s_nop 0
	global_load_lds_dwordx4 v130, s[6:7]
	s_add_i32 m0, s15, 0x16000
	s_nop 0
	global_load_lds_dwordx4 v134, s[6:7]
	s_add_u32 s6, s68, s0
	s_addc_u32 s7, s69, s1
	s_add_i32 s19, s15, 0x2000
	s_mov_b32 m0, s15
	s_add_u32 s0, s6, 0x40000
	global_load_lds_dwordx4 v128, s[6:7]
	s_mov_b32 m0, s19
	s_addc_u32 s1, s7, 0
	s_add_i32 s20, s15, 0x4000
	global_load_lds_dwordx4 v132, s[6:7]
	s_mov_b32 m0, s20
	s_add_i32 s21, s15, 0x6000
	global_load_lds_dwordx4 v128, s[0:1]
	s_mov_b32 m0, s21
	s_cmp_eq_u32 s22, 1
	global_load_lds_dwordx4 v132, s[0:1]
	s_cselect_b64 s[0:1], -1, 0
	s_cmp_lg_u32 s22, 1
	s_cbranch_scc1 .LBB0_1056
	s_setprio 1
	s_barrier
